# select phase: sub-key B fragments prefetched one key-block ahead instead of 6 serialized vmcnt(0) loads per block
# speedup vs baseline: 1.0021x; 1.0021x over previous
; __device__ __forceinline__ int crow(int r, int hi) { return (r & 3) + 8 * (r >> 2) + 4 * hi; }
; __device__ __forceinline__ void wave_lds_fence() { asm volatile("s_waitcnt lgkmcnt(0)" ::: "memory"); __builtin_amdgcn_wave_barrier(); asm volatile("" ::: "memory"); }
; __device__ __forceinline__ void scan_set(unsigned (&L)[16], const bf16_t* qbase  , const bf16_t* kbase  , float* buf, int lane) {
;     const int r32 = lane & 31, hi = lane >> 5;
; #pragma unroll
;     for (int p = 0; p < 16; ++p) L[p] = 0u;
;     bf16x8 a0[8], a1[8];
;     { const bf16_t* ap = qbase + (size_t)r32 * DM + hi * 8;
; #pragma unroll
;       for (int ks = 0; ks < 8; ++ks) { a0[ks] = *(const bf16x8*)(ap + ks * 16); a1[ks] = *(const bf16x8*)(ap + (size_t)32 * DM + ks * 16); } }
; #pragma unroll 1
;     for (int kb = 0; kb < 4; ++kb) {
;         f32x16 acc0 = {}, acc1 = {};
;         { const bf16_t* bp = kbase + (size_t)(kb * 32 + r32) * 128 + hi * 8;
;           bf16x8 b[8];
; #pragma unroll
;           for (int ks = 0; ks < 8; ++ks) b[ks] = *(const bf16x8*)(bp + ks * 16);
; #pragma unroll
;           for (int ks = 0; ks < 8; ++ks) { acc0 = __builtin_amdgcn_mfma_f32_32x32x16_bf16(a0[ks], b[ks], acc0, 0, 0, 0); acc1 = __builtin_amdgcn_mfma_f32_32x32x16_bf16(a1[ks], b[ks], acc1, 0, 0, 0); } }
;         wave_lds_fence();
; #pragma unroll
;         for (int r = 0; r < 16; ++r) { const int rowi = att::crow(r, hi); buf[rowi * 33 + r32] = acc0[r]; buf[(32 + rowi) * 33 + r32] = acc1[r]; }
;         wave_lds_fence();
.LBB0_2783:
	s_lshl_b32 s8, s12, 3
	s_andn2_b32 s8, s8, 63
	s_ashr_i32 s9, s8, 31
	v_mbcnt_lo_u32_b32 v104, -1, 0
	v_mbcnt_hi_u32_b32 v104, -1, v104
	s_lshl_b64 s[18:19], s[8:9], 12
	v_ashrrev_i32_e32 v4, 5, v104
	s_add_u32 s18, s15, s18
	v_and_b32_e32 v136, 31, v104
	v_lshlrev_b32_e32 v98, 3, v4
	s_addc_u32 s19, s16, s19
	v_lshlrev_b32_e32 v32, 12, v136
	v_ashrrev_i32_e32 v99, 31, v98
	v_lshl_add_u64 v[0:1], s[18:19], 0, v[32:33]
	v_lshlrev_b64 v[2:3], 1, v[98:99]
	v_lshl_add_u64 v[100:101], v[0:1], 0, v[2:3]
	v_add_co_u32_e32 v0, vcc, s66, v100
	v_lshl_add_u32 v105, v104, 5, v104
	s_nop 0
	v_addc_co_u32_e32 v1, vcc, 0, v101, vcc
	global_load_dwordx4 v[34:37], v[100:101], off
	global_load_dwordx4 v[38:41], v[100:101], off offset:32
	global_load_dwordx4 v[42:45], v[0:1], off
	global_load_dwordx4 v[46:49], v[0:1], off offset:32
	global_load_dwordx4 v[50:53], v[100:101], off offset:64
	global_load_dwordx4 v[54:57], v[100:101], off offset:96
	global_load_dwordx4 v[58:61], v[0:1], off offset:64
	global_load_dwordx4 v[62:65], v[0:1], off offset:96
	global_load_dwordx4 v[66:69], v[100:101], off offset:128
	global_load_dwordx4 v[70:73], v[100:101], off offset:160
	global_load_dwordx4 v[74:77], v[0:1], off offset:128
	global_load_dwordx4 v[78:81], v[0:1], off offset:160
	global_load_dwordx4 v[82:85], v[100:101], off offset:192
	global_load_dwordx4 v[86:89], v[100:101], off offset:224
	global_load_dwordx4 v[90:93], v[0:1], off offset:192
	global_load_dwordx4 v[94:97], v[0:1], off offset:224
	v_mul_lo_u32 v0, v4, s33
	v_lshlrev_b32_e32 v1, 2, v136
	s_mov_b32 s9, 0
	v_lshl_add_u64 v[102:103], s[4:5], 0, v[2:3]
	v_add3_u32 v107, s13, v0, v1
	v_add3_u32 v108, s13, v1, v0
	v_lshl_add_u32 v106, v105, 2, s13
	v_mov_b32_e32 v125, 0
	v_mov_b32_e32 v124, 0
	v_mov_b32_e32 v123, 0
	v_mov_b32_e32 v122, 0
	v_mov_b32_e32 v121, 0
	v_mov_b32_e32 v120, 0
	v_mov_b32_e32 v119, 0
	v_mov_b32_e32 v118, 0
	v_mov_b32_e32 v116, 0
	v_mov_b32_e32 v115, 0
	v_mov_b32_e32 v114, 0
	v_mov_b32_e32 v113, 0
	v_mov_b32_e32 v112, 0
	v_mov_b32_e32 v111, 0
	v_mov_b32_e32 v110, 0
	v_mov_b32_e32 v109, 0
	s_mov_b32 s18, 0
	v_lshlrev_b32_e32 v117, 7, v136
	v_mov_b32_e32 v32, v117
	v_lshl_add_u64 v[192:193], v[32:33], 1, v[102:103]
	global_load_dwordx4 v[160:163], v[192:193], off
	global_load_dwordx4 v[164:167], v[192:193], off offset:32
	global_load_dwordx4 v[168:171], v[192:193], off offset:64
	global_load_dwordx4 v[172:175], v[192:193], off offset:96
	global_load_dwordx4 v[176:179], v[192:193], off offset:128
	global_load_dwordx4 v[180:183], v[192:193], off offset:160
	global_load_dwordx4 v[184:187], v[192:193], off offset:192
	global_load_dwordx4 v[188:191], v[192:193], off offset:224
.LBB0_2784:
	v_add_u32_e32 v132, 0x1800, v107
	v_add_u32_e32 v133, 0x1a00, v107
	v_add_u32_e32 v134, 0xc00, v107
	v_add_u32_e32 v135, 0x1c00, v107
	s_mov_b32 s19, 0
	s_waitcnt vmcnt(0)
	v_mfma_f32_32x32x16_bf16 v[0:15], v[34:37], v[160:163], 0
	v_mfma_f32_32x32x16_bf16 v[16:31], v[42:45], v[160:163], 0
	v_mfma_f32_32x32x16_bf16 v[0:15], v[38:41], v[164:167], v[0:15]
	v_mfma_f32_32x32x16_bf16 v[16:31], v[46:49], v[164:167], v[16:31]
	v_mfma_f32_32x32x16_bf16 v[0:15], v[50:53], v[168:171], v[0:15]
	v_mfma_f32_32x32x16_bf16 v[16:31], v[58:61], v[168:171], v[16:31]
	v_mfma_f32_32x32x16_bf16 v[0:15], v[54:57], v[172:175], v[0:15]
	v_mfma_f32_32x32x16_bf16 v[16:31], v[62:65], v[172:175], v[16:31]
	v_mfma_f32_32x32x16_bf16 v[0:15], v[66:69], v[176:179], v[0:15]
	v_mfma_f32_32x32x16_bf16 v[16:31], v[74:77], v[176:179], v[16:31]
	v_mfma_f32_32x32x16_bf16 v[0:15], v[70:73], v[180:183], v[0:15]
	v_mfma_f32_32x32x16_bf16 v[16:31], v[78:81], v[180:183], v[16:31]
	v_add_u32_e32 v130, 0x1600, v107
	v_add_u32_e32 v131, 0x800, v107
	s_waitcnt lgkmcnt(0)
	v_mfma_f32_32x32x16_bf16 v[16:31], v[90:93], v[184:187], v[16:31]
	v_mfma_f32_32x32x16_bf16 v[0:15], v[82:85], v[184:187], v[0:15]
	v_add_u32_e32 v126, 0x1000, v107
	v_add_u32_e32 v127, 0x1200, v107
	v_add_u32_e32 v128, 0x400, v107
	v_add_u32_e32 v129, 0x1400, v107
	v_mfma_f32_32x32x16_bf16 v[16:31], v[94:97], v[188:191], v[16:31]
	v_mfma_f32_32x32x16_bf16 v[0:15], v[86:89], v[188:191], v[0:15]
	s_cmp_eq_u32 s18, 3
	s_cbranch_scc1 .Lsel_np_a
	s_add_i32 s20, s18, 1
	v_lshl_or_b32 v32, s20, 12, v117
	v_lshl_add_u64 v[192:193], v[32:33], 1, v[102:103]
	global_load_dwordx4 v[160:163], v[192:193], off
	global_load_dwordx4 v[164:167], v[192:193], off offset:32
	global_load_dwordx4 v[168:171], v[192:193], off offset:64
	global_load_dwordx4 v[172:175], v[192:193], off offset:96
	global_load_dwordx4 v[176:179], v[192:193], off offset:128
	global_load_dwordx4 v[180:183], v[192:193], off offset:160
	global_load_dwordx4 v[184:187], v[192:193], off offset:192
	global_load_dwordx4 v[188:191], v[192:193], off offset:224
.Lsel_np_a:
	s_nop 10
	ds_write_b32 v108, v16 offset:4224
	ds_write2_b32 v107, v0, v1 offset1:33
	ds_write2_b32 v126, v17, v18 offset0:65 offset1:98
	ds_write2_b32 v107, v2, v3 offset0:66 offset1:99
	ds_write2_b32 v127, v19, v20 offset0:3 offset1:168
	ds_write2_b32 v128, v4, v5 offset0:8 offset1:41
	ds_write2_b32 v129, v21, v22 offset0:73 offset1:106
	ds_write2_b32 v128, v6, v7 offset0:74 offset1:107
	ds_write2_b32 v130, v23, v24 offset0:11 offset1:176
	ds_write2_b32 v131, v8, v9 offset0:16 offset1:49
	ds_write2_b32 v132, v25, v26 offset0:81 offset1:114
	ds_write2_b32 v131, v10, v11 offset0:82 offset1:115
	ds_write2_b32 v133, v27, v28 offset0:19 offset1:184
	ds_write2_b32 v134, v12, v13 offset0:24 offset1:57
	ds_write2_b32 v135, v29, v30 offset0:89 offset1:122
	ds_write2_b32 v134, v14, v15 offset0:90 offset1:123
	ds_write_b32 v107, v31 offset:7788
	s_waitcnt lgkmcnt(0)
	v_mov_b32_e32 v0, v106
; __device__ __forceinline__ unsigned fkey(float f) { const unsigned b = __float_as_uint(f); return b ^ ((unsigned)((int)b >> 31) | 0x80000000u); }
; __device__ __forceinline__ unsigned umed3(unsigned a, unsigned b, unsigned c) { unsigned r; asm("v_med3_u32 %0, %1, %2, %3" : "=v"(r) : "v"(a), "v"(b), "v"(c)); return r; }
; __device__ __forceinline__ void kins16(unsigned (&L)[16], unsigned k) {
; #pragma unroll
;     for (int p = 15; p >= 1; --p) L[p] = umed3(L[p - 1], L[p], k);
;     L[0] = L[0] > k ? L[0] : k;
; }
; __device__ __forceinline__ void scan_set(unsigned (&L)[16], const bf16_t* qbase  , const bf16_t* kbase  , float* buf, int lane) {
;     ...
;         const unsigned tb = 127u - (unsigned)(kb * 32);
; #pragma unroll 8
;         for (int k = 0; k < 32; ++k) { unsigned code = tb - (unsigned)k; asm volatile("" : "+s"(code)); kins16(L, (fkey(buf[lane * 33 + k]) & ~127u) | code); }
.LBB0_2785:
	s_add_i32 s20, s9, s19
	s_add_i32 s21, s20, 0x7f
	ds_read_b32 v1, v0
	s_add_i32 s19, s19, -8
	s_waitcnt lgkmcnt(0)
	v_ashrrev_i32_e32 v2, 31, v1
	v_or_b32_e32 v2, 0x80000000, v2
	v_bitop3_b32 v1, v2, s60, v1 bitop3:0x48
	v_or_b32_e32 v1, s21, v1
	s_add_i32 s21, s20, 0x7e
	ds_read_b32 v17, v0 offset:4
	v_med3_u32 v2, v110, v109, v1
	v_med3_u32 v3, v111, v110, v1
	v_med3_u32 v4, v112, v111, v1
	v_med3_u32 v5, v113, v112, v1
	s_waitcnt lgkmcnt(0)
	v_ashrrev_i32_e32 v18, 31, v17
	v_or_b32_e32 v18, 0x80000000, v18
	v_bitop3_b32 v17, v18, s60, v17 bitop3:0x48
	v_med3_u32 v6, v114, v113, v1
	v_med3_u32 v7, v115, v114, v1
	v_med3_u32 v8, v116, v115, v1
	v_med3_u32 v9, v118, v116, v1
	v_med3_u32 v10, v119, v118, v1
	v_med3_u32 v11, v120, v119, v1
	v_med3_u32 v12, v121, v120, v1
	v_med3_u32 v13, v122, v121, v1
	v_med3_u32 v14, v123, v122, v1
	v_med3_u32 v15, v124, v123, v1
	v_med3_u32 v16, v125, v124, v1
	v_max_u32_e32 v1, v125, v1
	v_or_b32_e32 v17, s21, v17
	s_add_i32 s21, s20, 0x7d
	v_med3_u32 v2, v3, v2, v17
	v_med3_u32 v3, v4, v3, v17
	v_med3_u32 v4, v5, v4, v17
	v_med3_u32 v5, v6, v5, v17
	v_med3_u32 v6, v7, v6, v17
	v_med3_u32 v7, v8, v7, v17
	v_med3_u32 v8, v9, v8, v17
	v_med3_u32 v9, v10, v9, v17
	v_med3_u32 v10, v11, v10, v17
	v_med3_u32 v11, v12, v11, v17
	v_med3_u32 v12, v13, v12, v17
	v_med3_u32 v13, v14, v13, v17
	v_med3_u32 v14, v15, v14, v17
	v_med3_u32 v15, v16, v15, v17
	v_med3_u32 v16, v1, v16, v17
	v_max_u32_e32 v1, v1, v17
	ds_read_b32 v17, v0 offset:8
	s_waitcnt lgkmcnt(0)
	v_ashrrev_i32_e32 v18, 31, v17
	v_or_b32_e32 v18, 0x80000000, v18
	v_bitop3_b32 v17, v18, s60, v17 bitop3:0x48
	v_or_b32_e32 v17, s21, v17
	s_add_i32 s21, s20, 0x7c
	v_med3_u32 v2, v3, v2, v17
	v_med3_u32 v3, v4, v3, v17
	v_med3_u32 v4, v5, v4, v17
	v_med3_u32 v5, v6, v5, v17
	v_med3_u32 v6, v7, v6, v17
	v_med3_u32 v7, v8, v7, v17
	v_med3_u32 v8, v9, v8, v17
	v_med3_u32 v9, v10, v9, v17
	v_med3_u32 v10, v11, v10, v17
	v_med3_u32 v11, v12, v11, v17
	v_med3_u32 v12, v13, v12, v17
	v_med3_u32 v13, v14, v13, v17
	v_med3_u32 v14, v15, v14, v17
	v_med3_u32 v15, v16, v15, v17
	v_med3_u32 v16, v1, v16, v17
	v_max_u32_e32 v1, v1, v17
	ds_read_b32 v17, v0 offset:12
	s_waitcnt lgkmcnt(0)
	v_ashrrev_i32_e32 v18, 31, v17
	v_or_b32_e32 v18, 0x80000000, v18
	v_bitop3_b32 v17, v18, s60, v17 bitop3:0x48
	v_or_b32_e32 v17, s21, v17
	s_add_i32 s21, s20, 0x7b
	v_med3_u32 v2, v3, v2, v17
	v_med3_u32 v3, v4, v3, v17
	v_med3_u32 v4, v5, v4, v17
	v_med3_u32 v5, v6, v5, v17
	v_med3_u32 v6, v7, v6, v17
	v_med3_u32 v7, v8, v7, v17
	v_med3_u32 v8, v9, v8, v17
	v_med3_u32 v9, v10, v9, v17
	v_med3_u32 v10, v11, v10, v17
	v_med3_u32 v11, v12, v11, v17
	v_med3_u32 v12, v13, v12, v17
	v_med3_u32 v13, v14, v13, v17
	v_med3_u32 v14, v15, v14, v17
	v_med3_u32 v15, v16, v15, v17
	v_med3_u32 v16, v1, v16, v17
	v_max_u32_e32 v1, v1, v17
	ds_read_b32 v17, v0 offset:16
	s_waitcnt lgkmcnt(0)
	v_ashrrev_i32_e32 v18, 31, v17
	v_or_b32_e32 v18, 0x80000000, v18
	v_bitop3_b32 v17, v18, s60, v17 bitop3:0x48
	v_or_b32_e32 v17, s21, v17
	s_add_i32 s21, s20, 0x7a
	v_med3_u32 v2, v3, v2, v17
	v_med3_u32 v3, v4, v3, v17
	v_med3_u32 v4, v5, v4, v17
	v_med3_u32 v5, v6, v5, v17
	v_med3_u32 v6, v7, v6, v17
	v_med3_u32 v7, v8, v7, v17
	v_med3_u32 v8, v9, v8, v17
	v_med3_u32 v9, v10, v9, v17
	v_med3_u32 v10, v11, v10, v17
	v_med3_u32 v11, v12, v11, v17
	v_med3_u32 v12, v13, v12, v17
	v_med3_u32 v13, v14, v13, v17
	v_med3_u32 v14, v15, v14, v17
	v_med3_u32 v15, v16, v15, v17
	v_med3_u32 v16, v1, v16, v17
	v_max_u32_e32 v1, v1, v17
	ds_read_b32 v17, v0 offset:20
	s_waitcnt lgkmcnt(0)
	v_ashrrev_i32_e32 v18, 31, v17
	v_or_b32_e32 v18, 0x80000000, v18
	v_bitop3_b32 v17, v18, s60, v17 bitop3:0x48
	v_or_b32_e32 v17, s21, v17
	s_add_i32 s21, s20, 0x79
	v_med3_u32 v2, v3, v2, v17
	v_med3_u32 v3, v4, v3, v17
	v_med3_u32 v4, v5, v4, v17
	v_med3_u32 v5, v6, v5, v17
	v_med3_u32 v6, v7, v6, v17
	v_med3_u32 v7, v8, v7, v17
	v_med3_u32 v8, v9, v8, v17
	v_med3_u32 v9, v10, v9, v17
	v_med3_u32 v10, v11, v10, v17
	v_med3_u32 v11, v12, v11, v17
	v_med3_u32 v12, v13, v12, v17
	v_med3_u32 v13, v14, v13, v17
	v_med3_u32 v14, v15, v14, v17
	v_med3_u32 v15, v16, v15, v17
	v_med3_u32 v16, v1, v16, v17
	v_max_u32_e32 v1, v1, v17
	ds_read_b32 v17, v0 offset:24
	s_addk_i32 s20, 0x78
	s_cmpk_eq_i32 s19, 0xffe0
	s_waitcnt lgkmcnt(0)
	v_ashrrev_i32_e32 v18, 31, v17
	v_or_b32_e32 v18, 0x80000000, v18
	v_bitop3_b32 v17, v18, s60, v17 bitop3:0x48
	v_or_b32_e32 v17, s21, v17
	v_med3_u32 v2, v3, v2, v17
	v_med3_u32 v3, v4, v3, v17
	v_med3_u32 v4, v5, v4, v17
	v_med3_u32 v5, v6, v5, v17
	v_med3_u32 v6, v7, v6, v17
	v_med3_u32 v7, v8, v7, v17
	v_med3_u32 v8, v9, v8, v17
	v_med3_u32 v9, v10, v9, v17
	v_med3_u32 v10, v11, v10, v17
	v_med3_u32 v11, v12, v11, v17
	v_med3_u32 v12, v13, v12, v17
	v_med3_u32 v13, v14, v13, v17
	v_med3_u32 v14, v15, v14, v17
	v_med3_u32 v15, v16, v15, v17
	v_med3_u32 v16, v1, v16, v17
	v_max_u32_e32 v1, v1, v17
	ds_read_b32 v17, v0 offset:28
	v_add_u32_e32 v0, 32, v0
	s_waitcnt lgkmcnt(0)
	v_ashrrev_i32_e32 v18, 31, v17
	v_or_b32_e32 v18, 0x80000000, v18
	v_bitop3_b32 v17, v18, s60, v17 bitop3:0x48
	v_or_b32_e32 v17, s20, v17
	v_max_u32_e32 v125, v1, v17
	v_med3_u32 v109, v3, v2, v17
	v_med3_u32 v110, v4, v3, v17
	v_med3_u32 v111, v5, v4, v17
	v_med3_u32 v112, v6, v5, v17
	v_med3_u32 v113, v7, v6, v17
	v_med3_u32 v114, v8, v7, v17
	v_med3_u32 v115, v9, v8, v17
	v_med3_u32 v116, v10, v9, v17
	v_med3_u32 v118, v11, v10, v17
	v_med3_u32 v119, v12, v11, v17
	v_med3_u32 v120, v13, v12, v17
	v_med3_u32 v121, v14, v13, v17
	v_med3_u32 v122, v15, v14, v17
	v_med3_u32 v123, v16, v15, v17
	v_med3_u32 v124, v1, v16, v17
	s_cbranch_scc0 .LBB0_2785
; __device__ __forceinline__ void scan_set(unsigned (&L)[16], const bf16_t* qbase  , const bf16_t* kbase  , float* buf, int lane) {
;     ...
;     for (int p = 0; p < 16; ++p) L[p] = 0u;
;     bf16x8 a0[8], a1[8];
;     { const bf16_t* ap = qbase + (size_t)r32 * DM + hi * 8;
; #pragma unroll
;       for (int ks = 0; ks < 8; ++ks) { a0[ks] = *(const bf16x8*)(ap + ks * 16); a1[ks] = *(const bf16x8*)(ap + (size_t)32 * DM + ks * 16); } }
; #pragma unroll 1
;     for (int kb = 0; kb < 4; ++kb) {
;         f32x16 acc0 = {}, acc1 = {};
;         { const bf16_t* bp = kbase + (size_t)(kb * 32 + r32) * 128 + hi * 8;
;           bf16x8 b[8];
; #pragma unroll
;           for (int ks = 0; ks < 8; ++ks) b[ks] = *(const bf16x8*)(bp + ks * 16);
; #pragma unroll
;           for (int ks = 0; ks < 8; ++ks) { acc0 = __builtin_amdgcn_mfma_f32_32x32x16_bf16(a0[ks], b[ks], acc0, 0, 0, 0); acc1 = __builtin_amdgcn_mfma_f32_32x32x16_bf16(a1[ks], b[ks], acc1, 0, 0, 0); } }
; __device__ __forceinline__ void peer_select_unit(const Ctx& F, int layer, int u) {
;     ...
;         scan_set(Ka, PQ + (size_t)t0 * DM + h * 256, SK + (size_t)(h * 2) * 128 * 128, buf, lane);
;         scan_set(Kb, PQ + (size_t)t0 * DM + h * 256 + 128, SK + (size_t)(h * 2 + 1) * 128 * 128, buf, lane);
	s_add_i32 s18, s18, 1
	s_sub_i32 s9, s9, 32
	s_cmp_eq_u32 s18, 4
	s_cbranch_scc0 .LBB0_2784
	v_add_co_u32_e32 v0, vcc, 0x20000, v100
	s_mov_b32 s9, 0
	s_nop 0
	v_addc_co_u32_e32 v1, vcc, 0, v101, vcc
	global_load_dwordx4 v[34:37], v[100:101], off offset:256
	global_load_dwordx4 v[38:41], v[100:101], off offset:288
	global_load_dwordx4 v[42:45], v[0:1], off offset:256
	global_load_dwordx4 v[46:49], v[0:1], off offset:288
	global_load_dwordx4 v[50:53], v[100:101], off offset:320
	global_load_dwordx4 v[54:57], v[100:101], off offset:352
	global_load_dwordx4 v[58:61], v[0:1], off offset:320
	global_load_dwordx4 v[62:65], v[0:1], off offset:352
	global_load_dwordx4 v[66:69], v[100:101], off offset:384
	global_load_dwordx4 v[70:73], v[100:101], off offset:416
	global_load_dwordx4 v[74:77], v[0:1], off offset:384
	global_load_dwordx4 v[78:81], v[0:1], off offset:416
	global_load_dwordx4 v[82:85], v[100:101], off offset:448
	global_load_dwordx4 v[86:89], v[100:101], off offset:480
	global_load_dwordx4 v[90:93], v[0:1], off offset:448
	global_load_dwordx4 v[94:97], v[0:1], off offset:480
	v_lshl_add_u64 v[98:99], v[98:99], 1, s[6:7]
	v_mov_b32_e32 v140, 0
	v_mov_b32_e32 v147, 0
	v_mov_b32_e32 v146, 0
	v_mov_b32_e32 v145, 0
	v_mov_b32_e32 v144, 0
	v_mov_b32_e32 v143, 0
	v_mov_b32_e32 v142, 0
	v_mov_b32_e32 v141, 0
	v_mov_b32_e32 v100, 0
	v_mov_b32_e32 v101, 0
	v_mov_b32_e32 v102, 0
	v_mov_b32_e32 v103, 0
	v_mov_b32_e32 v136, 0
	v_mov_b32_e32 v137, 0
	v_mov_b32_e32 v138, 0
	v_mov_b32_e32 v139, 0
	s_mov_b32 s18, 0
	v_mov_b32_e32 v32, v117
	v_lshl_add_u64 v[192:193], v[32:33], 1, v[98:99]
	global_load_dwordx4 v[160:163], v[192:193], off
	global_load_dwordx4 v[164:167], v[192:193], off offset:32
	global_load_dwordx4 v[168:171], v[192:193], off offset:64
	global_load_dwordx4 v[172:175], v[192:193], off offset:96
	global_load_dwordx4 v[176:179], v[192:193], off offset:128
	global_load_dwordx4 v[180:183], v[192:193], off offset:160
	global_load_dwordx4 v[184:187], v[192:193], off offset:192
	global_load_dwordx4 v[188:191], v[192:193], off offset:224
.LBB0_2788:
	s_mov_b32 s19, 0
	s_waitcnt vmcnt(0)
	v_mfma_f32_32x32x16_bf16 v[0:15], v[34:37], v[160:163], 0
	v_mfma_f32_32x32x16_bf16 v[16:31], v[42:45], v[160:163], 0
	v_mfma_f32_32x32x16_bf16 v[0:15], v[38:41], v[164:167], v[0:15]
	v_mfma_f32_32x32x16_bf16 v[16:31], v[46:49], v[164:167], v[16:31]
	v_mfma_f32_32x32x16_bf16 v[0:15], v[50:53], v[168:171], v[0:15]
	v_mfma_f32_32x32x16_bf16 v[16:31], v[58:61], v[168:171], v[16:31]
	v_mfma_f32_32x32x16_bf16 v[0:15], v[54:57], v[172:175], v[0:15]
	v_mfma_f32_32x32x16_bf16 v[16:31], v[62:65], v[172:175], v[16:31]
	v_mfma_f32_32x32x16_bf16 v[0:15], v[66:69], v[176:179], v[0:15]
	v_mfma_f32_32x32x16_bf16 v[16:31], v[74:77], v[176:179], v[16:31]
	v_mfma_f32_32x32x16_bf16 v[0:15], v[70:73], v[180:183], v[0:15]
	v_mfma_f32_32x32x16_bf16 v[16:31], v[78:81], v[180:183], v[16:31]
	s_waitcnt lgkmcnt(0)
	v_mfma_f32_32x32x16_bf16 v[16:31], v[90:93], v[184:187], v[16:31]
	v_mfma_f32_32x32x16_bf16 v[0:15], v[82:85], v[184:187], v[0:15]
	v_mfma_f32_32x32x16_bf16 v[16:31], v[94:97], v[188:191], v[16:31]
	v_mfma_f32_32x32x16_bf16 v[0:15], v[86:89], v[188:191], v[0:15]
	s_cmp_eq_u32 s18, 3
	s_cbranch_scc1 .Lsel_np_b
	s_add_i32 s20, s18, 1
	v_lshl_or_b32 v32, s20, 12, v117
	v_lshl_add_u64 v[192:193], v[32:33], 1, v[98:99]
	global_load_dwordx4 v[160:163], v[192:193], off
	global_load_dwordx4 v[164:167], v[192:193], off offset:32
	global_load_dwordx4 v[168:171], v[192:193], off offset:64
	global_load_dwordx4 v[172:175], v[192:193], off offset:96
	global_load_dwordx4 v[176:179], v[192:193], off offset:128
	global_load_dwordx4 v[180:183], v[192:193], off offset:160
	global_load_dwordx4 v[184:187], v[192:193], off offset:192
	global_load_dwordx4 v[188:191], v[192:193], off offset:224
